# second differential / FoX unit of a workgroup: key-bias table kept from the unit before it, no table barrier, Q loads retire at the tile loop's first counted wait
# speedup vs baseline: 1.0045x; 1.0004x over previous
; template <int DV, int NMAP>
; __device__ __forceinline__ void attn_unit(LAS unsigned char* lds, const bf16_t* U, bf16_t* MIX, const float* logf, int b, int h, int qb, float lam, float slope2, const float* gn, float outscale, const int tid) {
;     ...
;     bf16x8 qr[4];
;     {
;         const bf16_t* qp = U + (rowbase + qrow0 + r32) * UW + qcol + map * 64 + hi * 8;
; #pragma unroll
;         for (int d0 = 0; d0 < 4; ++d0) qr[d0] = *(const bf16x8*)(qp + 16 * d0);
;     }
;     asm volatile("" : "+v"(qr[0]), "+v"(qr[1]), "+v"(qr[2]), "+v"(qr[3]));
;     const bf16_t* kg = U + (rowbase + lane) * UW + kcol + wid * 8;
;     const bf16_t* vg = U + (rowbase + 16 * (wid & 3) + (lane >> 2)) * UW + vcol + (wid >> 2) * 32 + (lane & 3) * 8;
;     const unsigned ldsb = (unsigned)(size_t)lds;
;     ...
;     __syncthreads();
;     AT_DMA(0, 0);
;     if (NT > 1) AT_DMA(1, 1);
;     const float m_run = bias[qrow0 + r32];
;     float l_run = 0.f;
;     f32x16 o[NDB];
; #pragma unroll
;     for (int d = 0; d < NDB; ++d)
; #pragma unroll
;         for (int r = 0; r < 16; ++r) o[d][r] = 0.f;
;     const int vofs = (4 * hi + ((lane & 15) >> 2)) * 64 + ((lane >> 4) & 1) * 32 + (lane & 3) * 8;
;     int st = 0, st2 = 2;
.Lfx_bias_done:
	s_lshl_b32 s36, s40, 5
	s_add_i32 s36, s36, s33
	s_lshr_b32 s37, s37, 6
	s_lshl_b32 s33, s60, 6
	s_ashr_i32 s30, s36, 31
	s_add_u32 s31, s36, s20
	v_or_b32_e32 v98, s31, v122
	v_mov_b64_e32 v[2:3], s[84:85]
	s_addc_u32 s61, s30, 0
	v_mad_u64_u32 v[2:3], s[30:31], v98, s87, v[2:3]
	v_mov_b32_e32 v0, 0x1800
	v_mad_i32_i24 v3, s61, v0, v3
	s_lshl_b32 s30, s60, 7
	s_mov_b32 s31, s21
	v_lshl_add_u64 v[2:3], v[2:3], 0, s[30:31]
	v_lshlrev_b32_e32 v0, 1, v126
	v_lshl_add_u64 v[2:3], v[2:3], 0, v[0:1]
	global_load_dwordx4 v[66:69], v[2:3], off offset:96
	global_load_dwordx4 v[70:73], v[2:3], off offset:64
	global_load_dwordx4 v[74:77], v[2:3], off offset:32
	global_load_dwordx4 v[78:81], v[2:3], off
	v_or_b32_e32 v0, s20, v123
	v_mul_u32_u24_e32 v0, 0xc00, v0
	v_lshlrev_b32_e32 v0, 1, v0
	v_lshl_add_u64 v[2:3], s[84:85], 0, v[0:1]
	s_lshl_b32 s60, s40, 3
	v_mov_b32_e32 v99, s61
	v_lshl_add_u64 v[2:3], v[2:3], 0, s[30:31]
	s_ashr_i32 s61, s60, 31
	v_lshl_add_u64 v[2:3], s[60:61], 1, v[2:3]
	s_mov_b64 s[60:61], 0x400
	v_lshl_add_u64 v[4:5], v[2:3], 0, s[60:61]
	s_bfe_u32 s60, s41, 0x20006
	v_lshl_or_b32 v0, s60, 4, v127
	v_or_b32_e32 v0, s20, v0
	v_mul_u32_u24_e32 v0, 0xc00, v0
	v_lshlrev_b32_e32 v0, 1, v0
	v_lshl_add_u64 v[6:7], s[84:85], 0, v[0:1]
	s_ashr_i32 s41, s41, 8
	v_lshl_add_u64 v[6:7], v[6:7], 0, s[30:31]
	s_lshl_b32 s30, s41, 5
	s_ashr_i32 s31, s30, 31
	s_mul_i32 s61, s40, 0x420
	v_lshl_add_u64 v[6:7], s[30:31], 1, v[6:7]
	s_add_i32 s20, s61, s49
	s_lshl_b32 s31, s60, 10
	v_lshlrev_b32_e32 v0, 1, v128
	v_lshl_add_u64 v[6:7], v[6:7], 0, v[0:1]
	v_lshl_add_u64 v[8:9], v[6:7], 0, s[50:51]
	v_or_b32_e32 v0, s36, v122
	v_mov_b32_e32 v105, 0
	s_or_b32 s60, s36, 31
	s_mov_b32 s64, 0
	v_mov_b32_e32 v106, v142
	s_mov_b32 s62, 0
	v_mov_b32_e32 v10, v105
	v_mov_b32_e32 v11, v105
	v_mov_b32_e32 v12, v105
	v_mov_b32_e32 v13, v105
	v_mov_b32_e32 v14, v105
	v_mov_b32_e32 v15, v105
	v_mov_b32_e32 v16, v105
	v_mov_b32_e32 v17, v105
	v_mov_b32_e32 v18, 0
	v_mov_b32_e32 v19, v105
	v_mov_b32_e32 v20, v105
	v_mov_b32_e32 v21, v105
	v_mov_b32_e32 v22, v105
	v_mov_b32_e32 v23, v105
	v_mov_b32_e32 v24, v105
	v_mov_b32_e32 v25, v105
	v_mov_b32_e32 v26, v105
	v_mov_b32_e32 v27, v105
	v_mov_b32_e32 v28, v105
	v_mov_b32_e32 v29, v105
	v_mov_b32_e32 v30, v105
	v_mov_b32_e32 v31, v105
	v_mov_b32_e32 v32, v105
	v_mov_b32_e32 v33, v105
	v_readlane_b32 s30, v255, 20
	s_waitcnt lgkmcnt(0)
	s_cmp_eq_u32 s30, 4
	s_cbranch_scc1 .Lfx_u2
	s_waitcnt vmcnt(0)
	s_barrier
.Lfx_u2:
	s_mov_b32 s30, m0
	s_mov_b32 m0, s20
	s_nop 0
	global_load_lds_dwordx4 v[4:5], off
	s_mov_b32 m0, s30
	s_lshl_b32 s30, s41, 12
	s_or_b32 s30, s31, s30
	s_add_i32 s41, s30, 0
	s_add_i32 s40, s41, 0x8400
	s_mov_b32 s30, m0
	s_mov_b32 m0, s40
	s_nop 0
	global_load_lds_dwordx4 v[8:9], off
	s_mov_b32 m0, s30
	s_mov_b64 s[30:31], 0x60400
	v_lshl_add_u64 v[4:5], v[2:3], 0, s[30:31]
	s_add_i32 s30, s61, 0
	s_addk_i32 s30, 0x4200
	s_mov_b32 s31, m0
	s_mov_b32 m0, s30
	s_nop 0
	global_load_lds_dwordx4 v[4:5], off
	s_mov_b32 m0, s31
	s_mov_b64 s[30:31], 0x60800
	v_lshl_add_u64 v[4:5], v[6:7], 0, s[30:31]
	s_add_i32 s41, s41, 0xa400
	s_mov_b32 s30, m0
	s_mov_b32 m0, s41
	s_nop 0
	global_load_lds_dwordx4 v[4:5], off
	s_mov_b32 m0, s30
	v_lshl_add_u32 v4, v0, 2, 0
	ds_read_b32 v104, v4
	s_mov_b64 s[30:31], 0xc0800
	v_lshl_add_u64 v[100:101], v[6:7], 0, s[30:31]
	s_mov_b64 s[30:31], 0xc0400
	s_mov_b32 s41, 2
	v_lshl_add_u64 v[102:103], v[2:3], 0, s[30:31]
	s_mov_b32 s61, 63
	v_mov_b32_e32 v2, 0
	v_mov_b32_e32 v3, v105
	v_mov_b32_e32 v4, v105
	v_mov_b32_e32 v5, v105
	v_mov_b32_e32 v6, v105
	v_mov_b32_e32 v7, v105
	v_mov_b32_e32 v8, v105
	v_mov_b32_e32 v9, v105
	s_add_i32 s63, s64, 1
	s_cmp_ge_u32 s63, s37
	s_mov_b64 s[30:31], -1
	s_cbranch_scc1 .LBB0_197

; template <int DV, int NMAP>
; __device__ __forceinline__ void attn_unit(LAS unsigned char* lds, const bf16_t* U, bf16_t* MIX, const float* logf, int b, int h, int qb, float lam, float slope2, const float* gn, float outscale, const int tid) {
;     ...
;         } else {
;             for (int s = tid; s < n; s += 512) bias[s] = slope2 * (float)s;
;         }
; __device__ __forceinline__ void attn_phase(const Args& a, int l, LAS unsigned char* lds, const int tid, const int rep) {
;     ...
;             const float slope2 = exp2f(-2.0f * (float)(h + 1)) * LOG2E;
.LBB0_206:
	s_and_b64 vcc, exec, s[30:31]
	s_cbranch_vccz .LBB0_176
	s_not_b32 s30, s27
	s_lshl_b32 s30, s30, 2
	s_and_b32 s62, s30, 0x780
	s_add_i32 s63, s62, 0x80
	s_and_b32 s20, s27, 3
	v_readfirstlane_b32 s33, v188
	v_readlane_b32 s36, v255, 20
	s_mov_b64 s[30:31], 0
	s_cmp_eq_u32 s36, 2
	s_cbranch_scc1 .LBB0_217
	v_cmp_gt_i32_e32 vcc, s63, v188
	s_and_saveexec_b64 s[30:31], vcc
	s_cbranch_execz .LBB0_217
	s_not_b32 s36, s20
	s_lshl_b32 s36, s36, 1
	v_ldexp_f32 v0, 1.0, s36
	v_mul_f32_e32 v2, 0x3fb8aa3b, v0
	v_max_i32_e32 v0, s63, v189
	v_add_u32_e32 v4, v0, v145
	s_movk_i32 s36, 0x1ff
	v_cmp_lt_u32_e32 vcc, s36, v4
	s_mov_b64 s[40:41], -1
	v_mov_b32_e32 v0, v188
	v_mov_b32_e32 v3, v124
	s_and_saveexec_b64 s[36:37], vcc
	s_cbranch_execz .LBB0_214
	v_lshrrev_b32_e32 v0, 9, v4
	v_add_u32_e32 v0, 1, v0
	v_and_b32_e32 v6, 0xfffffe, v0
	v_mov_b32_e32 v3, v2
	s_mov_b64 s[40:41], 0
	v_mov_b32_e32 v7, v6
	v_mov_b32_e32 v8, v129
	v_mov_b64_e32 v[4:5], v[188:189]

; template <int DV, int NMAP>
; __device__ __forceinline__ void attn_unit(LAS unsigned char* lds, const bf16_t* U, bf16_t* MIX, const float* logf, int b, int h, int qb, float lam, float slope2, const float* gn, float outscale, const int tid) {
;     ...
;     bf16x8 qr[4];
;     {
;         const bf16_t* qp = U + (rowbase + qrow0 + r32) * UW + qcol + map * 64 + hi * 8;
; #pragma unroll
;         for (int d0 = 0; d0 < 4; ++d0) qr[d0] = *(const bf16x8*)(qp + 16 * d0);
;     }
;     asm volatile("" : "+v"(qr[0]), "+v"(qr[1]), "+v"(qr[2]), "+v"(qr[3]));
;     const bf16_t* kg = U + (rowbase + lane) * UW + kcol + wid * 8;
;     const bf16_t* vg = U + (rowbase + 16 * (wid & 3) + (lane >> 2)) * UW + vcol + (wid >> 2) * 32 + (lane & 3) * 8;
;     const unsigned ldsb = (unsigned)(size_t)lds;
;     ...
;     __syncthreads();
;     AT_DMA(0, 0);
;     if (NT > 1) AT_DMA(1, 1);
.LBB0_217:
	s_or_b64 exec, exec, s[30:31]
	s_ashr_i32 s36, s33, 6
	s_and_b32 s61, s36, 3
	s_lshl_b32 s27, s27, 9
	s_lshl_b32 s30, s61, 5
	s_and_b32 s37, s27, 0x3800
	s_or_b32 s62, s30, s62
	v_or_b32_e32 v0, s37, v122
	v_or_b32_e32 v147, s62, v0
	v_mov_b64_e32 v[2:3], s[84:85]
	s_ashr_i32 s60, s33, 8
	v_mad_u64_u32 v[2:3], s[30:31], v147, s87, v[2:3]
	s_lshl_b32 s27, s20, 7
	s_lshl_b32 s20, s20, 8
	s_lshl_b32 s30, s60, 6
	v_lshl_add_u64 v[2:3], v[2:3], 0, s[20:21]
	s_ashr_i32 s31, s30, 31
	v_lshl_add_u64 v[2:3], s[30:31], 1, v[2:3]
	v_lshlrev_b32_e32 v0, 1, v126
	v_lshl_add_u64 v[2:3], v[2:3], 0, v[0:1]
	global_load_dwordx4 v[98:101], v[2:3], off offset:3168
	global_load_dwordx4 v[102:105], v[2:3], off offset:3136
	global_load_dwordx4 v[106:109], v[2:3], off offset:3104
	global_load_dwordx4 v[110:113], v[2:3], off offset:3072
	v_or_b32_e32 v0, s37, v123
	v_mul_u32_u24_e32 v0, 0xc00, v0
	v_lshlrev_b32_e32 v0, 1, v0
	s_lshl_b32 s30, s36, 3
	v_lshl_add_u64 v[2:3], s[84:85], 0, v[0:1]
	s_ashr_i32 s31, s30, 31
	v_lshl_add_u64 v[2:3], v[2:3], 0, s[20:21]
	s_lshl_b64 s[40:41], s[30:31], 1
	s_mul_i32 s65, s36, 0x420
	v_lshl_add_u64 v[4:5], v[2:3], 0, s[40:41]
	v_lshl_or_b32 v2, s61, 4, v127
	s_add_i32 s67, s65, 0
	v_lshl_add_u64 v[6:7], v[4:5], 0, s[22:23]
	v_or_b32_e32 v2, s37, v2
	s_add_i32 s64, s67, 0x2100
	v_mul_u32_u24_e32 v2, 0xc00, v2
	v_lshlrev_b32_e32 v2, 1, v2
	v_mov_b32_e32 v3, v1
	s_lshl_b32 s30, s60, 5
	v_lshl_add_u64 v[8:9], s[84:85], 0, v[2:3]
	s_ashr_i32 s31, s30, 31
	v_lshl_add_u64 v[8:9], v[8:9], 0, s[20:21]
	s_lshr_b32 s63, s63, 6
	v_or_b32_e32 v148, s62, v122
	v_mov_b32_e32 v14, v1
	v_mov_b32_e32 v15, v1
	v_mov_b32_e32 v10, v1
	v_mov_b32_e32 v11, v1
	v_mov_b32_e32 v12, v1
	v_mov_b32_e32 v13, v1
	v_mov_b32_e32 v150, 0
	v_mov_b32_e32 v151, v142
	v_readlane_b32 s30, v255, 20
	s_nop 0
	s_cmp_eq_u32 s30, 2
	s_cbranch_scc1 .Ldf_u2
	s_waitcnt vmcnt(0)
	s_waitcnt lgkmcnt(0)
	s_barrier
.Ldf_u2:
	s_mov_b32 s41, m0
	s_mov_b32 s68, s36
	s_mov_b32 s65, s60
	s_or_b32 s40, s62, 31
	s_lshr_b32 s40, s40, 6
	s_mov_b32 s37, 0
	v_mov_b64_e32 v[118:119], v[6:7]
	s_lshl_b32 s30, s60, 6
	s_mov_b32 s31, 0
	v_lshl_add_u64 v[138:139], v[8:9], 0, s[30:31]
	v_lshlrev_b32_e32 v116, 1, v128
	v_mov_b32_e32 v117, 0
	v_lshl_add_u64 v[138:139], v[138:139], 0, v[116:117]
	s_mov_b64 s[30:31], 0x1400
	v_lshl_add_u64 v[138:139], v[138:139], 0, s[30:31]
	v_and_b32_e32 v180, 7, v123
	v_sub_u32_e32 v180, v180, v123
	s_lshl_b32 s30, s68, 3
	v_add_u32_e32 v180, s30, v180
	v_mul_i32_i24_e32 v180, 0x1800, v180
	v_lshrrev_b32_e32 v181, 3, v123
	v_subrev_u32_e32 v181, s68, v181
	v_lshl_add_u32 v180, v181, 4, v180
	v_ashrrev_i32_e32 v181, 31, v180
	v_lshl_add_u64 v[136:137], v[118:119], 0, v[180:181]
	v_bfe_u32 v180, v123, 2, 3
	v_lshrrev_b32_e32 v181, 2, v123
	v_sub_u32_e32 v180, v180, v181
	s_and_b32 s31, s68, 3
	s_lshl_b32 s31, s31, 4
	s_lshl_b32 s30, s68, 3
	s_sub_i32 s30, s30, s31
	v_add_u32_e32 v180, s30, v180
	v_mul_i32_i24_e32 v180, 0x1800, v180
	v_lshrrev_b32_e32 v181, 5, v123
	s_lshr_b32 s31, s68, 2
	v_subrev_u32_e32 v181, s31, v181
	v_lshl_add_u32 v180, v181, 6, v180
	v_ashrrev_i32_e32 v181, 31, v180
	v_lshl_add_u64 v[138:139], v[138:139], 0, v[180:181]
	s_lshr_b32 s30, s68, 2
	s_mul_i32 s30, s30, 0x1080
	s_and_b32 s31, s68, 3
	s_lshl_b32 s31, s31, 10
	s_add_i32 s30, s30, s31
	s_bfe_u32 s31, s68, 0x10001
	s_lshl_b32 s31, s31, 7
	s_add_i32 s30, s30, s31
	s_add_i32 s64, s30, 0x2100
	s_mul_i32 s30, s68, 0x800
	s_add_i32 s66, s30, 0x12900
	v_lshrrev_b32_e32 v180, 3, v122
	v_lshlrev_b32_e32 v180, 10, v180
	v_bfe_u32 v181, v122, 4, 1
	v_lshl_add_u32 v180, v181, 7, v180
	v_lshrrev_b32_e32 v181, 5, v123
	v_lshl_add_u32 v180, v181, 7, v180
	v_and_b32_e32 v181, 7, v122
	v_lshl_add_u32 v244, v181, 4, v180
	v_lshl_add_u32 v121, v148, 2, 0
	s_mov_b32 s30, 0
	s_cmp_ge_u32 s30, s63
	s_cbranch_scc1 .Ldf_nkp0
	s_and_b32 s31, s30, 3
	s_mul_i32 s31, s31, 0x4200
	s_add_i32 s31, s31, s64
	s_mov_b32 m0, s31
	v_lshl_add_u64 v[116:117], v[136:137], 0, s[24:25]
	global_load_lds_dwordx4 v[136:137], off
	s_add_i32 m0, s31, 0x2100
	v_lshl_add_u64 v[136:137], v[136:137], 0, s[28:29]
	global_load_lds_dwordx4 v[116:117], off
